# loop-edge edits: MFMA-result padding moved to the no-prefetch path in A/B sweeps; single back-branch in D loop
# baseline (speedup 1.0000x reference)
; DI void attn_item(const Params& P, unsigned char* smem, bool samp, int b, int c) {
;     ...
;     for (int kt = 0; kt < ntiles; ++kt) {
;       float sc[4][2];
;       IDX_PIPE_STEP(kt, sc);
.LBB0_300:
	s_waitcnt vmcnt(0)
	v_mfma_f32_32x32x16_bf16 v[20:35], v[44:47], v[68:71], 0
	s_cmp_ge_u32 s14, s95
	v_mfma_f32_32x32x16_bf16 v[4:19], v[44:47], v[84:87], 0
	v_mfma_f32_32x32x16_bf16 v[20:35], v[36:39], v[92:95], v[20:35]
	v_mfma_f32_32x32x16_bf16 v[4:19], v[36:39], v[72:75], v[4:19]
	v_mfma_f32_32x32x16_bf16 v[20:35], v[40:43], v[80:83], v[20:35]
	v_mfma_f32_32x32x16_bf16 v[4:19], v[40:43], v[88:91], v[4:19]
	v_mfma_f32_32x32x16_bf16 v[20:35], v[48:51], v[96:99], v[20:35]
	v_mfma_f32_32x32x16_bf16 v[4:19], v[48:51], v[76:79], v[4:19]
	s_cbranch_scc1 .LnopA
	v_lshl_add_u64 v[68:69], v[114:115], 0, s[2:3]
	v_add_co_u32_e32 v76, vcc, 0x2000, v68
	s_nop 1
	v_addc_co_u32_e32 v77, vcc, 0, v69, vcc
	v_add_co_u32_e32 v78, vcc, 0x3000, v68
	s_nop 1
	v_addc_co_u32_e32 v79, vcc, 0, v69, vcc
	global_load_dwordx4 v[68:71], v[76:77], off
	global_load_dwordx4 v[92:95], v[76:77], off offset:1024
	global_load_dwordx4 v[84:87], v[78:79], off
	global_load_dwordx4 v[72:75], v[78:79], off offset:1024
	global_load_dwordx4 v[80:83], v[76:77], off offset:2048
	global_load_dwordx4 v[96:99], v[76:77], off offset:3072
	global_load_dwordx4 v[88:91], v[78:79], off offset:2048
	s_nop 0
	global_load_dwordx4 v[76:79], v[78:79], off offset:3072
	s_branch .LBB0_302

; #define IDX_PIPE_BEGIN() bf16x8 nk0[4], nk1[4]; IDX_LOAD(0, nk0, nk1);
; DI int score_bin(float s, float isg) {
;   const float a = fabsf(s) * isg;
;   const int e = (int)(__float_as_uint(a) >> 18) - ((130 << 5) - 256);
;   const int ec = (e + 192) >> 2;
;   int k = e >= 64 ? e : ec;
;   k = k < 0 ? 0 : (k > 254 ? 254 : k);
;   return (s > 0.f) ? (256 + k) : ((s < 0.f) ? (254 - k) : 255);
; DI void attn_item(const Params& P, unsigned char* smem, bool samp, int b, int c) {
;     ...
;     for (int i = lane; i < 2048; i += 64) hist[i] = 0u;
;     { IDX_PIPE_BEGIN();
; #pragma unroll 1
;     for (int kt = 0; kt < ntiles; ++kt) {
;       float sc[4][2];
;       IDX_PIPE_STEP(kt, sc);
;       if (kt * 64 + 64 <= nkeys) {
;         for (int hf = 0; hf < 2; ++hf)
;           for (int i = 0; i < 4; ++i) {
;             const int bn = score_bin(sc[i][hf], scl[i]);
;             atomicAdd(&hist[(g + 2 * i) * 256 + (bn >> 1)], 1u << (16 * (bn & 1)));
.LBB0_302:
	v_med3_f32 v139, v20, 0, v187
	v_med3_f32 v138, v24, 0, v187
	v_med3_f32 v21, v21, 0, v187
	v_med3_f32 v20, v25, 0, v187
	v_pk_mul_f32 v[24:25], v[120:121], v[138:139]
	v_med3_f32 v141, v22, 0, v187
	v_med3_f32 v140, v26, 0, v187
	v_pk_fma_f32 v[20:21], v[122:123], v[20:21], v[24:25]
	v_med3_f32 v23, v23, 0, v187
	v_pk_fma_f32 v[20:21], v[124:125], v[140:141], v[20:21]
	v_med3_f32 v22, v27, 0, v187
	v_pk_fma_f32 v[22:23], v[126:127], v[22:23], v[20:21]
	v_med3_f32 v21, v28, 0, v187
	v_med3_f32 v20, v32, 0, v187
	v_med3_f32 v25, v29, 0, v187
	v_med3_f32 v24, v33, 0, v187
	v_pk_mul_f32 v[20:21], v[128:129], v[20:21]
	v_med3_f32 v27, v30, 0, v187
	v_med3_f32 v26, v34, 0, v187
	v_pk_fma_f32 v[20:21], v[130:131], v[24:25], v[20:21]
	v_med3_f32 v29, v31, 0, v187
	v_pk_fma_f32 v[20:21], v[132:133], v[26:27], v[20:21]
	v_med3_f32 v28, v35, 0, v187
	s_cmp_gt_u32 s13, s1
	v_pk_fma_f32 v[20:21], v[134:135], v[28:29], v[20:21]
	s_cbranch_scc1 .LBB0_304
	v_and_b32_e32 v25, 0x7fffffff, v23
	v_and_b32_e32 v24, 0x7fffffff, v22
	v_pk_mul_f32 v[24:25], v[102:103], v[24:25]
	s_nop 0
	v_lshrrev_b32_e32 v26, 18, v25
	v_add_u32_e32 v27, 0xfffff0c0, v26
	v_add_u32_e32 v26, 0xfffff180, v26
	v_ashrrev_i32_e32 v26, 2, v26
	v_cmp_lt_u32_e32 vcc, s92, v25
	s_mov_b64 s[8:9], -1
	s_nop 0
	v_cndmask_b32_e32 v25, v26, v27, vcc
	v_med3_i32 v25, v25, 0, v188
	v_or_b32_e32 v26, 0x100, v25
	v_sub_u32_e32 v25, 0xfe, v25
	v_cmp_gt_f32_e32 vcc, 0, v23
	s_nop 1
	v_cndmask_b32_e32 v25, v189, v25, vcc
	v_cmp_lt_f32_e32 vcc, 0, v23
	s_nop 1
	v_cndmask_b32_e32 v25, v25, v26, vcc
	v_lshlrev_b32_e32 v26, 1, v25
	v_and_b32_e32 v26, 0x3fc, v26
	v_lshlrev_b32_e32 v25, 4, v25
	v_add_u32_e32 v26, v136, v26
	v_lshlrev_b32_e64 v25, v25, 1
	ds_add_u32 v26, v25
	v_lshrrev_b32_e32 v25, 18, v24
	v_add_u32_e32 v26, 0xfffff0c0, v25
	v_add_u32_e32 v25, 0xfffff180, v25
	v_ashrrev_i32_e32 v25, 2, v25
	v_cmp_lt_u32_e32 vcc, s92, v24
	s_nop 1
	v_cndmask_b32_e32 v24, v25, v26, vcc
	v_med3_i32 v24, v24, 0, v188
	v_or_b32_e32 v25, 0x100, v24
	v_sub_u32_e32 v24, 0xfe, v24
	v_cmp_gt_f32_e32 vcc, 0, v22
	s_nop 1
	v_cndmask_b32_e32 v24, v189, v24, vcc
	v_cmp_lt_f32_e32 vcc, 0, v22
	s_nop 1
	v_cndmask_b32_e32 v24, v24, v25, vcc
	v_lshlrev_b32_e32 v25, 1, v24
	v_and_b32_e32 v25, 0x3fc, v25
	v_lshlrev_b32_e32 v24, 4, v24
	v_add_u32_e32 v25, v136, v25
	v_lshlrev_b32_e64 v24, v24, 1
	ds_add_u32 v25, v24 offset:2048
	v_and_b32_e32 v25, 0x7fffffff, v21
	v_and_b32_e32 v24, 0x7fffffff, v20
	v_pk_mul_f32 v[24:25], v[106:107], v[24:25]
	s_nop 0
	v_lshrrev_b32_e32 v26, 18, v25
	v_add_u32_e32 v27, 0xfffff0c0, v26
	v_add_u32_e32 v26, 0xfffff180, v26
	v_ashrrev_i32_e32 v26, 2, v26
	v_cmp_lt_u32_e32 vcc, s92, v25
	s_nop 1
	v_cndmask_b32_e32 v25, v26, v27, vcc
	v_med3_i32 v25, v25, 0, v188
	v_or_b32_e32 v26, 0x100, v25
	v_sub_u32_e32 v25, 0xfe, v25
	v_cmp_gt_f32_e32 vcc, 0, v21
	s_nop 1
	v_cndmask_b32_e32 v25, v189, v25, vcc
	v_cmp_lt_f32_e32 vcc, 0, v21
	s_nop 1
	v_cndmask_b32_e32 v25, v25, v26, vcc
	v_lshlrev_b32_e32 v26, 1, v25
	v_and_b32_e32 v26, 0x3fc, v26
	v_lshlrev_b32_e32 v25, 4, v25
	v_add_u32_e32 v26, v136, v26
	v_lshlrev_b32_e64 v25, v25, 1
	ds_add_u32 v26, v25 offset:4096
	v_lshrrev_b32_e32 v25, 18, v24
	v_add_u32_e32 v26, 0xfffff0c0, v25
	v_add_u32_e32 v25, 0xfffff180, v25
	v_ashrrev_i32_e32 v25, 2, v25
	v_cmp_lt_u32_e32 vcc, s92, v24
	s_nop 1
	v_cndmask_b32_e32 v24, v25, v26, vcc
	v_med3_i32 v24, v24, 0, v188
	v_or_b32_e32 v25, 0x100, v24
	v_sub_u32_e32 v24, 0xfe, v24
	v_cmp_gt_f32_e32 vcc, 0, v20
	s_nop 1
	v_cndmask_b32_e32 v24, v189, v24, vcc
	v_cmp_lt_f32_e32 vcc, 0, v20
	s_nop 1
	v_cndmask_b32_e32 v24, v24, v25, vcc
	v_lshlrev_b32_e32 v25, 1, v24
	v_and_b32_e32 v25, 0x3fc, v25
	v_lshlrev_b32_e32 v24, 4, v24
	v_add_u32_e32 v25, v136, v25
	v_lshlrev_b32_e64 v24, v24, 1
	ds_add_u32 v25, v24 offset:6144
	s_cbranch_execz .LBB0_305
	s_branch .LBB0_308

; DI void attn_item(const Params& P, unsigned char* smem, bool samp, int b, int c) {
;     ...
;       for (int kt = 0; kt < ntiles; ++kt) {
;         float sc[4][2];
;         IDX_PIPE_STEP(kt, sc);
.LBB0_618:
	s_waitcnt vmcnt(0)
	v_mfma_f32_32x32x16_bf16 v[20:35], v[44:47], v[76:79], 0
	s_add_i32 s96, s96, 1
	s_cmp_ge_u32 s96, s95
	v_mfma_f32_32x32x16_bf16 v[4:19], v[44:47], v[80:83], 0
	v_mfma_f32_32x32x16_bf16 v[20:35], v[36:39], v[88:91], v[20:35]
	v_mfma_f32_32x32x16_bf16 v[4:19], v[36:39], v[84:87], v[4:19]
	v_mfma_f32_32x32x16_bf16 v[20:35], v[40:43], v[92:95], v[20:35]
	v_mfma_f32_32x32x16_bf16 v[4:19], v[40:43], v[96:99], v[4:19]
	v_mfma_f32_32x32x16_bf16 v[20:35], v[48:51], v[104:107], v[20:35]
	v_mfma_f32_32x32x16_bf16 v[4:19], v[48:51], v[100:103], v[4:19]
	s_cbranch_scc1 .LnopB
	v_add_co_u32_e32 v76, vcc, 0xffffe400, v116
	s_nop 1
	v_addc_co_u32_e32 v77, vcc, -1, v117, vcc
	v_add_co_u32_e32 v80, vcc, 0xfffff400, v116
	s_nop 1
	v_addc_co_u32_e32 v81, vcc, -1, v117, vcc
	v_add_co_u32_e32 v84, vcc, 0xffffe800, v116
	global_load_dwordx4 v[76:79], v[76:77], off
	s_nop 0
	global_load_dwordx4 v[80:83], v[80:81], off
	v_addc_co_u32_e32 v85, vcc, -1, v117, vcc
	v_add_co_u32_e32 v86, vcc, 0xfffff800, v116
	s_nop 1
	v_addc_co_u32_e32 v87, vcc, -1, v117, vcc
	v_add_co_u32_e32 v92, vcc, 0xffffec00, v116
	global_load_dwordx4 v[88:91], v[84:85], off
	s_nop 0
	global_load_dwordx4 v[84:87], v[86:87], off
	v_addc_co_u32_e32 v93, vcc, -1, v117, vcc
	v_add_co_u32_e32 v96, vcc, 0xfffffc00, v116
	s_nop 1
	v_addc_co_u32_e32 v97, vcc, -1, v117, vcc
	v_add_co_u32_e32 v100, vcc, 0xfffff000, v116
	global_load_dwordx4 v[92:95], v[92:93], off
	s_nop 0
	global_load_dwordx4 v[96:99], v[96:97], off
	v_addc_co_u32_e32 v101, vcc, -1, v117, vcc
	global_load_dwordx4 v[104:107], v[100:101], off
	s_nop 0
	global_load_dwordx4 v[100:103], v[116:117], off
	s_branch .LBB0_620

; DI unsigned mono_key(float s) {
;   unsigned u = __float_as_uint(s);
;   return (u & 0x80000000u) ? ~u : (u | 0x80000000u);
; }
; DI void attn_item(const Params& P, unsigned char* smem, bool samp, int b, int c) {
;     ...
;         const bool tail = (kt * 64 + 64 > nkeys);
;         unsigned mv = 0u;
;         for (int hf = 0; hf < 2; ++hf) {
;           const bool valid = !tail || ((kt * 64 + hf * 32 + l32) < nkeys);
;           for (int i = 0; i < 4; ++i) {
;             const unsigned key = mono_key(sc[i][hf]);
;             bool sel = valid && (key >= khi[i]);
;             const bool inb = valid && (key >= klo[i]) && (key < khi[i]);
;             const bool zb = (bst[i] == 255);
;             if (anyzb) {
;               const unsigned long long bal = __ballot(inb && zb);
;               const unsigned mym = g ? (unsigned)(bal >> 32) : (unsigned)bal;
;               const int rank = __popc(mym & ltmask);
;               sel = sel || (inb && zb && (seen[i] + rank < nd[i]));
;               seen[i] += __popc(mym);
;             }
;             const bool cand = inb && !zb;
;             const unsigned long long cb = __ballot(cand);
;             if (cb != 0ull) {
;               const unsigned mym = g ? (unsigned)(cb >> 32) : (unsigned)cb;
;               const int slot = cbase[i] + __popc(mym & ltmask);
;               if (cand && slot < CAND_CAP)
;                 lst[(g + 2 * i) * CAND_CAP + slot] = make_uint2(key, (unsigned)(kt * 64 + hf * 32 + l32));
;               cbase[i] += __popc(mym);
;             }
.LBB0_620:
	v_med3_f32 v20, v20, 0, v187
	v_mul_f32_e32 v20, v52, v20
	v_med3_f32 v21, v21, 0, v187
	v_fmac_f32_e32 v20, v53, v21
	v_med3_f32 v21, v22, 0, v187
	v_fmac_f32_e32 v20, v54, v21
	v_med3_f32 v21, v23, 0, v187
	v_fmac_f32_e32 v20, v55, v21
	s_cmp_le_u32 s21, s1
	v_add_u32_e32 v21, s21, v195
	s_cselect_b64 s[68:69], -1, 0
	v_cmp_gt_u32_e32 vcc, s0, v21
	s_or_b64 s[66:67], s[68:69], vcc
	v_not_b32_e32 v22, v20
	v_or_b32_e32 v23, 0x80000000, v20
	v_cmp_gt_i32_e32 vcc, 0, v20
	s_nop 1
	v_cndmask_b32_e32 v20, v23, v22, vcc
	v_cmp_ge_u32_e32 vcc, v20, v69
	s_and_b64 s[62:63], s[66:67], vcc
	v_cmp_ge_u32_e32 vcc, v20, v68
	s_and_b64 s[58:59], s[66:67], vcc
	v_cmp_lt_u32_e32 vcc, v20, v69
	v_cndmask_b32_e64 v22, 0, 1, s[88:89]
	s_and_b64 s[64:65], s[58:59], vcc
	v_cmp_ne_u32_e64 s[58:59], 1, v22
	s_andn2_b64 vcc, exec, s[88:89]
	s_cbranch_vccnz .LBB0_622
	s_and_b64 vcc, s[18:19], s[64:65]
	s_mov_b64 s[60:61], vcc
	s_nop 0
	v_cndmask_b32_e64 v126, 0, 1, s[62:63]
	s_nop 0
	v_lshrrev_b64 v[22:23], v114, s[60:61]
	v_and_b32_e32 v23, v22, v109
	v_bcnt_u32_b32 v23, v23, v124
	v_cmp_lt_i32_e64 s[60:61], v23, v121
	v_bcnt_u32_b32 v124, v22, v124
	s_nop 0
	v_cndmask_b32_e64 v23, 0, 1, s[60:61]
	v_cndmask_b32_e32 v23, v126, v23, vcc
	v_and_b32_e32 v23, 1, v23
	v_cmp_eq_u32_e32 vcc, 1, v23
	s_andn2_b64 s[60:61], s[62:63], exec
	s_and_b64 s[62:63], vcc, exec
	s_or_b64 s[62:63], s[60:61], s[62:63]

; DI void attn_item(const Params& P, unsigned char* smem, bool samp, int b, int c) {
;     ...
;       float ps = 0.f;
;       for (int r = 0; r < 16; ++r) {
;         const float p = __builtin_amdgcn_exp2f(sacc[qh][r] - mcur);
;         sacc[qh][r] = p;
;         ps += p;
;       }
;       lrun[qh] += ps;
;     ...
;     if (hh + 1 < nhalf) {
;       const u16* vp = vbase + (long)(hh + 1) * 16384;
;       for (int dh = 0; dh < 2; ++dh)
;         for (int s = 0; s < 2; ++s) vfN[dh][s] = ld16(vp + (s * 2 + dh) * 512);
;     }
.LBB0_709:
	v_pk_add_f32 v[92:93], v[92:93], v[94:95]
	v_pk_add_f32 v[6:7], v[6:7], v[8:9]
	v_pk_add_f32 v[96:97], v[96:97], v[98:99]
	v_pk_add_f32 v[10:11], v[10:11], v[12:13]
	v_pk_add_f32 v[84:85], v[84:85], v[86:87]
	v_pk_add_f32 v[14:15], v[14:15], v[16:17]
	v_add_f32_e32 v100, v100, v91
	v_add_f32_e32 v5, v5, v90
	v_pk_add_f32 v[92:93], v[92:93], v[96:97]
	v_pk_add_f32 v[6:7], v[6:7], v[10:11]
	v_pk_add_f32 v[82:83], v[82:83], v[84:85]
	v_pk_add_f32 v[14:15], v[14:15], v[88:89]
	v_pk_add_f32 v[92:93], v[92:93], v[82:83]
	v_pk_add_f32 v[6:7], v[6:7], v[14:15]
	s_add_i32 s8, s8, 32
	v_add_f32_e32 v92, v92, v93
	v_add_f32_e32 v6, v6, v7
	v_add_f32_e32 v92, v92, v100
	v_add_f32_e32 v5, v5, v6
	v_add_f32_e32 v197, v197, v92
	v_add_f32_e32 v4, v4, v5
	v_lshl_add_u64 v[178:179], v[178:179], 0, s[82:83]
	v_lshl_add_u64 v[180:181], v[180:181], 0, s[82:83]
	v_add_u32_e32 v199, 0x80, v199
	s_cmp_lg_u32 s9, s11
	v_add_u32_e32 v200, 0x100, v200
	s_mov_b32 s2, s11
	s_cbranch_scc1 .LBB0_697
